# speedup vs baseline: 1.0037x; 1.0002x over previous
; DI void attn_item(const P& p, int l, int item, char* smem) {
;     ...
;   for (int kt = -1; kt < 128; ++kt) {
;     if (kt + 1 < 128) {
;       u16* Kd = Ks + ((kt + 1) & 1) * (256 * 72);
;       u16* Vd = Kd + 2 * 64 * 72;
; #pragma unroll
;       for (int i = 0; i < 2; ++i) {
;         const int row = tid >> 3, kc = tid & 7;
;         *(u32x4*)(Kd + (i * 64 + row) * 72 + kc * 8) = kreg[i];
;       }
; #pragma unroll
;       for (int i = 0; i < 2; ++i) {
;         const int cid = tid + NT * i;
;         const int e = cid >> 3, kc = cid & 7;
;         uint2 w0; w0.x = vreg[i][0]; w0.y = vreg[i][1];
;         uint2 w1; w1.x = vreg[i][2]; w1.y = vreg[i][3];
;         u16* vd = Vd + e * 72 + (kc >> 1) * 16 + (kc & 1) * 4;
;         *(uint2*)vd = w0;
;         *(uint2*)(vd + 8) = w1;
;       }
;     }
;     if (kt + 2 < 128) {
;       const int kn = kt + 2;
; #pragma unroll
;       for (int i = 0; i < 2; ++i) kreg[i] = *(const u32x4*)(kbase + ((size_t)i * SEQ + kn * 64) * 64 + tid * 8);
; #pragma unroll
;       for (int i = 0; i < 2; ++i) {
;         const int cid = tid + NT * i;
;         const int e = cid >> 3, kc = cid & 7;
;         vreg[i] = *(const u32x4*)(vbase + (size_t)e * VTP + kn * 64 + kc * 8);
;       }
;     }
;     __builtin_amdgcn_sched_barrier(0x38F);
;     if (kt >= 0) {
;       const u16* Kc = Ks + (kt & 1) * (256 * 72);
;       const u16* Vc = Kc + 2 * 64 * 72;
;       bf16x8 kf[8];
; #pragma unroll
;       for (int i = 0; i < 8; ++i)
;         kf[i] = *(const bf16x8*)(Kc + (c * 64 + 32 * (i & 1) + li) * 72 + 16 * (i >> 1) + 8 * g);
;       u32x4 vf[16];
; #pragma unroll
;       for (int i = 0; i < 16; ++i) {
;         const int eb = i & 3, s = (i >> 2) & 1, kb = i >> 3;
;         vf[i] = *(const u32x4*)(Vc + (32 * eb + li) * 72 + 32 * kb + 16 * s + 8 * g);
;       }
;       f32x16 S[2];
; #pragma unroll
;       for (int kb = 0; kb < 2; ++kb)
; #pragma unroll
;         for (int r = 0; r < 16; ++r) S[kb][r] = negm;
; #pragma unroll
;       for (int i = 0; i < 8; ++i) S[i & 1] = MFMA(kf[i], qf[i >> 1], S[i & 1]);
;       u32x4 pk[4];
;       float sum = 0.f;
; #pragma unroll
;       for (int ch = 0; ch < 4; ++ch) {
;         const int kb = ch >> 1, s = ch & 1;
; #pragma unroll
;         for (int j2 = 0; j2 < 4; ++j2) {
;           const float p0 = __builtin_amdgcn_exp2f(S[kb][8 * s + 2 * j2]);
.Lat_exit:
	global_load_dwordx4 v[232:235], v[148:149], off
	global_load_dwordx4 v[228:231], v[156:157], off
	global_load_dwordx4 v[236:239], v[146:147], off
	global_load_dwordx4 v[240:243], v[144:145], off
	v_add_f32_e32 v167, v167, v88
	v_add_f32_e32 v190, v190, v89
	v_add_f32_e32 v191, v191, v90
	v_add_f32_e32 v196, v196, v91
	v_add_f32_e32 v167, v167, v92
	v_add_f32_e32 v190, v190, v93
	v_add_f32_e32 v191, v191, v94
	v_add_f32_e32 v196, v196, v95
	v_add_f32_e64 v167, v167, v190
	v_add_f32_e64 v191, v191, v196
	s_nop 0
	v_add_f32_e64 v167, v167, v191
	v_mov_b32_e32 v176, v168
	v_add_u32_e32 v177, 0xd800, v169
	v_add_u32_e32 v178, 0xd800, v143
	v_add3_u32 v129, 0, v175, v188
	ds_read_b128 v[80:83], v129
	ds_read_b128 v[130:133], v129 offset:4608
	v_add3_u32 v128, 0, v174, v188
	ds_read_b128 v[134:137], v128 offset:18432
	v_readlane_b32 s6, v248, 5
	s_waitcnt lgkmcnt(2)
	v_mfma_f32_32x32x16_bf16 v[96:111], v[80:83], v[112:115], v[16:31]
	s_waitcnt lgkmcnt(1)
	v_mfma_f32_32x32x16_bf16 v[80:95], v[130:133], v[112:115], v[16:31]
	ds_read_b128 v[130:133], v129 offset:32
	s_waitcnt lgkmcnt(0)
	v_mfma_f32_32x32x16_bf16 v[96:111], v[130:133], v[116:119], v[96:111]
	ds_read_b128 v[130:133], v129 offset:4640
	s_waitcnt lgkmcnt(0)
	v_mfma_f32_32x32x16_bf16 v[80:95], v[130:133], v[116:119], v[80:95]
	ds_read_b128 v[130:133], v129 offset:64
	s_waitcnt lgkmcnt(0)
	v_mfma_f32_32x32x16_bf16 v[96:111], v[130:133], v[124:127], v[96:111]
	ds_read_b128 v[130:133], v129 offset:4672
	s_waitcnt lgkmcnt(0)
	v_mfma_f32_32x32x16_bf16 v[80:95], v[130:133], v[124:127], v[80:95]
	ds_read_b128 v[130:133], v129 offset:96
	s_waitcnt lgkmcnt(0)
	v_mfma_f32_32x32x16_bf16 v[96:111], v[130:133], v[120:123], v[96:111]
	ds_read_b128 v[130:133], v129 offset:4704
	s_nop 10
	v_exp_f32_e32 v144, v100
	v_exp_f32_e32 v145, v101
	v_exp_f32_e32 v146, v102
	v_exp_f32_e32 v147, v103
	ds_read_b128 v[100:103], v128 offset:23040
	v_exp_f32_e32 v138, v96
	v_exp_f32_e32 v139, v97
	v_exp_f32_e32 v142, v98
	v_exp_f32_e32 v143, v99
	v_cvt_pk_bf16_f32 v98, v144, v145
	v_cvt_pk_bf16_f32 v96, v138, v139
	v_cvt_pk_bf16_f32 v99, v146, v147
	v_cvt_pk_bf16_f32 v97, v142, v143
	v_exp_f32_e32 v108, v108
	v_exp_f32_e32 v109, v109
	s_waitcnt lgkmcnt(0)
	v_mfma_f32_32x32x16_bf16 v[48:63], v[100:103], v[96:99], v[48:63]
	ds_read_b128 v[100:103], v128 offset:27648
	v_exp_f32_e32 v110, v110
	v_exp_f32_e32 v111, v111
	v_mfma_f32_32x32x16_bf16 v[80:95], v[130:133], v[120:123], v[80:95]
	s_waitcnt lgkmcnt(0)
	v_mfma_f32_32x32x16_bf16 v[32:47], v[100:103], v[96:99], v[32:47]
	ds_read_b128 v[100:103], v128 offset:32256
	ds_read_b128 v[130:133], v128 offset:18464
	s_nop 7
	v_exp_f32_e32 v148, v84
	v_exp_f32_e32 v149, v85
	v_exp_f32_e32 v150, v86
	v_exp_f32_e32 v151, v87
	v_exp_f32_e32 v152, v88
	v_exp_f32_e32 v153, v89
	s_waitcnt lgkmcnt(1)
	v_mfma_f32_32x32x16_bf16 v[0:15], v[100:103], v[96:99], v[0:15]
	ds_read_b128 v[100:103], v128 offset:23072
	v_exp_f32_e32 v154, v90
	v_exp_f32_e32 v155, v91
	v_exp_f32_e32 v156, v92
	v_exp_f32_e32 v157, v93
	v_exp_f32_e32 v168, v94
	v_exp_f32_e32 v169, v95
	v_mfma_f32_32x32x16_bf16 v[64:79], v[134:137], v[96:99], v[64:79]
	v_exp_f32_e32 v134, v104
	v_exp_f32_e32 v135, v105
	v_exp_f32_e32 v136, v106
	v_exp_f32_e32 v137, v107
	v_cvt_pk_bf16_f32 v98, v108, v109
	v_cvt_pk_bf16_f32 v96, v134, v135
	v_cvt_pk_bf16_f32 v99, v110, v111
	v_cvt_pk_bf16_f32 v97, v136, v137
	v_add_f32_e32 v88, v165, v166
	v_mul_f32_e32 v165, 0x3fb8aa3b, v88
	s_waitcnt lgkmcnt(0)
	v_mfma_f32_32x32x16_bf16 v[48:63], v[100:103], v[96:99], v[48:63]
	ds_read_b128 v[100:103], v128 offset:27680
	v_add_f32_e32 v134, v134, v135
	s_waitcnt lgkmcnt(0)
	v_mfma_f32_32x32x16_bf16 v[32:47], v[100:103], v[96:99], v[32:47]
	ds_read_b128 v[100:103], v128 offset:32288
	ds_read_b128 v[104:107], v128 offset:18496
	ds_read_b128 v[84:87], v128 offset:23104
	v_mfma_f32_32x32x16_bf16 v[64:79], v[130:133], v[96:99], v[64:79]
	v_exp_f32_e32 v130, v80
	v_exp_f32_e32 v131, v81
	v_exp_f32_e32 v132, v82
	v_exp_f32_e32 v133, v83
	v_cvt_pk_bf16_f32 v82, v148, v149
	v_cvt_pk_bf16_f32 v80, v130, v131
	v_cvt_pk_bf16_f32 v83, v150, v151
	v_cvt_pk_bf16_f32 v81, v132, v133
	s_waitcnt lgkmcnt(2)
	v_mfma_f32_32x32x16_bf16 v[0:15], v[100:103], v[96:99], v[0:15]
	s_waitcnt lgkmcnt(0)
	v_mfma_f32_32x32x16_bf16 v[48:63], v[84:87], v[80:83], v[48:63]
	ds_read_b128 v[84:87], v128 offset:27712
	s_waitcnt lgkmcnt(0)
	v_mfma_f32_32x32x16_bf16 v[32:47], v[84:87], v[80:83], v[32:47]
	ds_read_b128 v[84:87], v128 offset:32320
	ds_read_b128 v[96:99], v128 offset:18528
	s_waitcnt lgkmcnt(1)
	v_mfma_f32_32x32x16_bf16 v[0:15], v[84:87], v[80:83], v[0:15]
	ds_read_b128 v[84:87], v128 offset:23136
	v_mfma_f32_32x32x16_bf16 v[64:79], v[104:107], v[80:83], v[64:79]
	v_cvt_pk_bf16_f32 v80, v152, v153
	v_cvt_pk_bf16_f32 v81, v154, v155
	v_cvt_pk_bf16_f32 v82, v156, v157
	v_cvt_pk_bf16_f32 v83, v168, v169
	s_waitcnt lgkmcnt(0)
	s_nop 0
	v_mfma_f32_32x32x16_bf16 v[48:63], v[84:87], v[80:83], v[48:63]
	ds_read_b128 v[84:87], v128 offset:27744
	s_waitcnt lgkmcnt(0)
	v_mfma_f32_32x32x16_bf16 v[32:47], v[84:87], v[80:83], v[32:47]
	s_waitcnt vmcnt(0)
	ds_write_b128 v176, v[228:231] offset:36864
	ds_write_b128 v176, v[232:235] offset:46080
	ds_write2_b64 v177, v[236:237], v[238:239] offset1:2
	ds_write2_b64 v178, v[240:241], v[242:243] offset1:2
	ds_read_b128 v[84:87], v128 offset:32352
	s_waitcnt lgkmcnt(0)
	s_barrier
; #define MFMA(a, b, c) __builtin_amdgcn_mfma_f32_32x32x16_bf16((a), (b), (c), 0, 0, 0)
; DI void attn_item(const P& p, int l, int item, char* smem) {
;     ...
;     if (kt >= 0) {
;       const u16* Kc = Ks + (kt & 1) * (256 * 72);
;       const u16* Vc = Kc + 2 * 64 * 72;
;       bf16x8 kf[8];
; #pragma unroll
;       for (int i = 0; i < 8; ++i)
;         kf[i] = *(const bf16x8*)(Kc + (c * 64 + 32 * (i & 1) + li) * 72 + 16 * (i >> 1) + 8 * g);
;       u32x4 vf[16];
; #pragma unroll
;       for (int i = 0; i < 16; ++i) {
;         const int eb = i & 3, s = (i >> 2) & 1, kb = i >> 3;
;         vf[i] = *(const u32x4*)(Vc + (32 * eb + li) * 72 + 32 * kb + 16 * s + 8 * g);
;       }
;       f32x16 S[2];
; #pragma unroll
;       for (int kb = 0; kb < 2; ++kb)
; #pragma unroll
;         for (int r = 0; r < 16; ++r) S[kb][r] = negm;
; #pragma unroll
;       for (int i = 0; i < 8; ++i) S[i & 1] = MFMA(kf[i], qf[i >> 1], S[i & 1]);
;       u32x4 pk[4];
;       float sum = 0.f;
; #pragma unroll
;       for (int ch = 0; ch < 4; ++ch) {
;         const int kb = ch >> 1, s = ch & 1;
; #pragma unroll
;         for (int j2 = 0; j2 < 4; ++j2) {
;           const float p0 = __builtin_amdgcn_exp2f(S[kb][8 * s + 2 * j2]);
;           const float p1 = __builtin_amdgcn_exp2f(S[kb][8 * s + 2 * j2 + 1]);
;           sum += p0 + p1;
;           pk[ch][j2] = pack2(p0, p1);
;         }
;       }
;       ls += sum;
; #pragma unroll
;       for (int i = 0; i < 16; ++i) {
;         const int eb = i & 3, ch = i >> 2;
;         O[eb] = MFMA(__builtin_bit_cast(bf16x8, vf[i]), __builtin_bit_cast(bf16x8, pk[ch]), O[eb]);
;       }
;     }
	v_mfma_f32_32x32x16_bf16 v[64:79], v[96:99], v[80:83], v[64:79]
	ds_read_b128 v[96:99], v129 offset:36864
	ds_read_b128 v[100:103], v129 offset:41472
	ds_read_b128 v[104:107], v129 offset:36896
	v_mfma_f32_32x32x16_bf16 v[0:15], v[84:87], v[80:83], v[0:15]
	v_add_f32_e32 v80, v138, v139
	v_add_f32_e32 v80, 0, v80
	v_add_f32_e32 v81, v142, v143
	v_add_f32_e32 v138, v81, v80
	v_exp_f32_e32 v139, v165
	s_waitcnt lgkmcnt(2)
	v_mfma_f32_32x32x16_bf16 v[80:95], v[96:99], v[112:115], v[16:31]
	v_add_f32_e32 v96, v144, v145
	v_add_f32_e32 v96, v96, v138
	v_add_f32_e32 v97, v146, v147
	v_add_f32_e32 v138, v97, v96
	v_add_f32_e32 v134, v134, v138
	ds_read_b128 v[96:99], v129 offset:41504
	s_waitcnt lgkmcnt(2)
	v_mfma_f32_32x32x16_bf16 v[16:31], v[100:103], v[112:115], v[16:31]
	v_add_f32_e32 v100, v136, v137
	v_add_f32_e32 v100, v100, v134
	v_add_f32_e32 v101, v108, v109
	v_add_f32_e32 v100, v101, v100
	v_add_f32_e32 v101, v110, v111
	v_add_f32_e32 v100, v101, v100
	v_add_f32_e32 v101, v130, v131
	v_add_f32_e32 v100, v101, v100
	v_add_f32_e32 v101, v132, v133
	s_waitcnt lgkmcnt(1)
	v_mfma_f32_32x32x16_bf16 v[80:95], v[104:107], v[116:119], v[80:95]
	v_add_f32_e32 v104, v101, v100
	ds_read_b128 v[100:103], v129 offset:36928
	v_add_f32_e32 v105, v148, v149
	v_add_f32_e32 v104, v105, v104
	v_add_f32_e32 v105, v150, v151
	v_add_f32_e32 v108, v105, v104
	v_add_f32_e32 v109, v152, v153
	s_waitcnt lgkmcnt(0)
	v_mfma_f32_32x32x16_bf16 v[80:95], v[100:103], v[124:127], v[80:95]
	v_add_f32_e32 v110, v154, v155
	v_add_f32_e32 v100, v109, v108
	v_add_f32_e32 v111, v156, v157
	v_add_f32_e32 v100, v110, v100
	v_add_f32_e32 v112, v168, v169
	v_add_f32_e32 v100, v111, v100
	v_add_f32_e32 v108, v112, v100
	v_mfma_f32_32x32x16_bf16 v[16:31], v[96:99], v[116:119], v[16:31]
	ds_read_b128 v[96:99], v129 offset:41536
	ds_read_b128 v[104:107], v129 offset:36960
	ds_read_b128 v[100:103], v129 offset:41568
	v_add_f32_e32 v129, v167, v108
	v_add_f32_e32 v108, v163, v164
	v_mul_f32_e32 v138, 0x3fb8aa3b, v108
	v_add_u32_e32 v150, 0xd800, v128
	s_waitcnt lgkmcnt(1)
	v_mfma_f32_32x32x16_bf16 v[80:95], v[104:107], v[120:123], v[80:95]
	v_mfma_f32_32x32x16_bf16 v[16:31], v[96:99], v[124:127], v[16:31]
	s_nop 10
	v_exp_f32_e32 v154, v80
	v_exp_f32_e32 v155, v81
	v_exp_f32_e32 v156, v82
	v_exp_f32_e32 v157, v83
	v_exp_f32_e32 v163, v84
	v_exp_f32_e32 v164, v85
	v_exp_f32_e32 v165, v86
	v_exp_f32_e32 v166, v87
	ds_read_b128 v[96:99], v128 offset:55296
	ds_read_b128 v[108:111], v128 offset:55328
	ds_read_b128 v[112:115], v128 offset:59904
	ds_read_b128 v[116:119], v128 offset:59936
	s_waitcnt lgkmcnt(4)
	v_mfma_f32_32x32x16_bf16 v[16:31], v[100:103], v[120:123], v[16:31]
	ds_read_b128 v[84:87], v128 offset:64512
	ds_read_b128 v[100:103], v128 offset:64544
	v_cvt_pk_bf16_f32 v80, v154, v155
	v_cvt_pk_bf16_f32 v81, v156, v157
	v_cvt_pk_bf16_f32 v82, v163, v164
	v_cvt_pk_bf16_f32 v83, v165, v166
	s_nop 5
	v_exp_f32_e32 v16, v16
	s_waitcnt lgkmcnt(5)
	v_mfma_f32_32x32x16_bf16 v[64:79], v[96:99], v[80:83], v[64:79]
	ds_read_b128 v[96:99], v150 offset:13824
	ds_read_b128 v[104:107], v150 offset:13856
	ds_read_b128 v[120:123], v128 offset:55360
	ds_read_b128 v[124:127], v128 offset:55392
	ds_read_b128 v[130:133], v128 offset:59968
	ds_read_b128 v[134:137], v128 offset:60000
	ds_read_b128 v[142:145], v128 offset:64576
	v_exp_f32_e32 v17, v17
	v_exp_f32_e32 v18, v18
	v_exp_f32_e32 v19, v19
	v_exp_f32_e32 v20, v20
	v_exp_f32_e32 v21, v21
	v_exp_f32_e32 v22, v22
	s_waitcnt lgkmcnt(10)
	v_mfma_f32_32x32x16_bf16 v[48:63], v[112:115], v[80:83], v[48:63]
	ds_read_b128 v[112:115], v128 offset:64608
	ds_read_b128 v[146:149], v150 offset:13888
	ds_read_b128 v[150:153], v150 offset:13920
	v_add_f32_e32 v128, v154, v155
	v_add_f32_e32 v128, 0, v128
	v_add_f32_e32 v154, v156, v157
	v_add_f32_e32 v128, v154, v128
	v_exp_f32_e32 v23, v23
	s_waitcnt lgkmcnt(0)
	v_mfma_f32_32x32x16_bf16 v[32:47], v[84:87], v[80:83], v[32:47]
	v_exp_f32_e32 v85, v88
	v_exp_f32_e32 v86, v89
	v_exp_f32_e32 v87, v90
	v_exp_f32_e32 v88, v91
	v_add_f32_e32 v84, v163, v164
	v_exp_f32_e32 v89, v92
	v_exp_f32_e32 v90, v93
	v_add_f32_e32 v84, v84, v128
	v_mfma_f32_32x32x16_bf16 v[0:15], v[96:99], v[80:83], v[0:15]
	v_exp_f32_e32 v91, v94
	v_exp_f32_e32 v92, v95
	v_add_f32_e32 v93, v165, v166
	v_cvt_pk_bf16_f32 v80, v85, v86
	v_add_f32_e32 v84, v93, v84
	v_add_f32_e32 v85, v85, v86
	v_add_f32_e32 v84, v85, v84
	v_add_f32_e32 v85, v87, v88
	v_add_f32_e32 v84, v85, v84
	v_add_f32_e32 v85, v89, v90
	v_add_f32_e32 v84, v85, v84
	v_add_f32_e32 v85, v91, v92
	v_add_f32_e32 v84, v85, v84
	v_add_f32_e32 v85, v16, v17
	v_add_f32_e32 v84, v85, v84
	v_cvt_pk_bf16_f32 v16, v16, v17
	v_add_f32_e32 v17, v18, v19
	v_cvt_pk_bf16_f32 v81, v87, v88
	v_cvt_pk_bf16_f32 v82, v89, v90
	v_cvt_pk_bf16_f32 v83, v91, v92
	v_add_f32_e32 v84, v17, v84
	v_cvt_pk_bf16_f32 v17, v18, v19
	v_add_f32_e32 v18, v20, v21
	v_mfma_f32_32x32x16_bf16 v[64:79], v[108:111], v[80:83], v[64:79]
	v_cvt_pk_bf16_f32 v19, v22, v23
	s_barrier
; #define MFMA(a, b, c) __builtin_amdgcn_mfma_f32_32x32x16_bf16((a), (b), (c), 0, 0, 0)
; DI void attn_item(const P& p, int l, int item, char* smem) {
;     ...
;       for (int i = 0; i < 16; ++i) {
;         const int eb = i & 3, ch = i >> 2;
;         O[eb] = MFMA(__builtin_bit_cast(bf16x8, vf[i]), __builtin_bit_cast(bf16x8, pk[ch]), O[eb]);
;       }
;     }
;     __syncthreads();
;   }
;   const float lt = ls + __shfl_xor(ls, 32);
;   const float inv = (c == 0) ? (1.0f / lt) : (lam / lt);
;   float* exch = (float*)smem + qg * (64 * 64);
;   if (c == 1) {
; #pragma unroll
;     for (int eb = 0; eb < 4; ++eb)
; #pragma unroll
;       for (int r = 0; r < 16; ++r) exch[(eb * 16 + r) * 64 + lane] = O[eb][r] * inv;
;   }
;   __syncthreads();
;   if (c == 0) {
;     float ss = 0.f;
; #pragma unroll
;     for (int eb = 0; eb < 4; ++eb)
; #pragma unroll
;       for (int r = 0; r < 16; ++r) {
;         const float o = O[eb][r] * inv - exch[(eb * 16 + r) * 64 + lane];
;         O[eb][r] = o;
;         ss += o * o;
;       }
;     ss += __shfl_xor(ss, 32);
;     const float rn = rsqrtf(ss * (1.0f / 128.0f) + 1e-5f) * (1.0f - lam_init);
;     const size_t tok = (size_t)b * SEQ + tq;
; #pragma unroll
;     for (int eb = 0; eb < 4; ++eb)
; #pragma unroll
;       for (int rq = 0; rq < 4; ++rq) {
;         const int e = 32 * eb + 8 * rq + 4 * g;
;         const uint2 gt = *(const uint2*)(p.AG + tok * 512 + h * 128 + e);
;         const float4 sg = *(const float4*)(p.subg + l * 128 + e);
	v_mfma_f32_32x32x16_bf16 v[48:63], v[116:119], v[80:83], v[48:63]
	v_mfma_f32_32x32x16_bf16 v[32:47], v[100:103], v[80:83], v[32:47]
	v_mfma_f32_32x32x16_bf16 v[0:15], v[104:107], v[80:83], v[0:15]
	v_add_f32_e32 v80, v18, v84
	v_cvt_pk_bf16_f32 v18, v20, v21
	v_add_f32_e32 v20, v22, v23
	v_exp_f32_e32 v21, v24
	v_exp_f32_e32 v22, v25
	v_exp_f32_e32 v23, v26
	v_exp_f32_e32 v25, v27
	v_add_f32_e32 v24, v20, v80
	v_add_f32_e32 v26, v21, v22
	v_cvt_pk_bf16_f32 v20, v21, v22
	v_add_f32_e32 v27, v23, v25
	v_cvt_pk_bf16_f32 v21, v23, v25
	v_exp_f32_e32 v22, v28
	v_exp_f32_e32 v23, v29
	v_exp_f32_e32 v25, v30
	v_exp_f32_e32 v28, v31
	v_add_f32_e32 v24, v26, v24
	v_add_f32_e32 v29, v22, v23
	v_add_f32_e32 v24, v27, v24
	v_add_f32_e32 v30, v25, v28
	v_add_f32_e32 v24, v29, v24
	v_mfma_f32_32x32x16_bf16 v[64:79], v[120:123], v[16:19], v[64:79]
	v_cvt_pk_bf16_f32 v22, v22, v23
	v_cvt_pk_bf16_f32 v23, v25, v28
	v_mfma_f32_32x32x16_bf16 v[48:63], v[130:133], v[16:19], v[48:63]
	v_mfma_f32_32x32x16_bf16 v[32:47], v[142:145], v[16:19], v[32:47]
	v_mfma_f32_32x32x16_bf16 v[0:15], v[146:149], v[16:19], v[0:15]
	v_add_f32_e32 v16, v30, v24
	v_exp_f32_e32 v17, v138
	v_add_f32_e32 v16, v129, v16
	ds_bpermute_b32 v18, v158, v16
	v_sub_f32_e32 v17, v17, v139
	v_add_f32_e32 v17, s6, v17
	s_movk_i32 s6, 0x100
	v_cmp_gt_u32_e64 s[6:7], s6, v161
	s_waitcnt lgkmcnt(0)
	v_add_f32_e32 v16, v16, v18
	v_mfma_f32_32x32x16_bf16 v[64:79], v[124:127], v[20:23], v[64:79]
	v_cndmask_b32_e64 v17, v17, 1.0, s[6:7]
	v_div_scale_f32 v18, s[10:11], v16, v16, v17
	v_rcp_f32_e32 v19, v18
	s_nop 0
	v_fma_f32 v24, -v18, v19, 1.0
	v_mfma_f32_32x32x16_bf16 v[48:63], v[134:137], v[20:23], v[48:63]
	v_fmac_f32_e32 v19, v24, v19
	v_div_scale_f32 v24, vcc, v17, v16, v17
	v_mul_f32_e32 v25, v24, v19
	v_fma_f32 v26, -v18, v25, v24
	v_fmac_f32_e32 v25, v26, v19
	v_fma_f32 v18, -v18, v25, v24
	v_mfma_f32_32x32x16_bf16 v[32:47], v[112:115], v[20:23], v[32:47]
	v_div_fmas_f32 v18, v18, v19, v25
	v_div_fixup_f32 v80, v18, v16, v17
	v_lshl_add_u32 v16, v162, 14, 0
	v_cmp_eq_u32_e32 vcc, 1, v160
	v_lshl_add_u32 v18, v141, 2, v16
	v_mfma_f32_32x32x16_bf16 v[0:15], v[150:153], v[20:23], v[0:15]
	s_and_saveexec_b64 s[10:11], s[6:7]
	s_cbranch_execz .Lfin_nl
	v_and_b32_e32 v142, 15, v161
	v_bfe_u32 v143, v161, 4, 2
	v_and_b32_e32 v144, 0xffffffe0, v140
	v_add_u32_e32 v144, v144, v143
	s_lshl_b32 s56, s12, 11
	s_and_b32 s56, s56, 0x2000
	v_add_u32_e32 v144, s56, v144
	v_lshlrev_b32_e32 v144, 10, v144
	s_lshl_b32 s56, s95, 8
	s_and_b32 s56, s56, 0x300
	v_add_u32_e32 v144, s56, v144
	v_lshl_add_u32 v144, v142, 4, v144
	v_mov_b32_e32 v147, v144
	v_lshlrev_b32_e32 v145, 5, v142
	global_load_dwordx4 v[100:103], v145, s[30:31]
	global_load_dwordx4 v[104:107], v145, s[30:31] offset:16
	global_load_dwordx4 v[228:231], v144, s[44:45]
	v_add_u32_e32 v144, 0x1000, v144
	global_load_dwordx4 v[232:235], v144, s[44:45]
	v_add_u32_e32 v144, 0x1000, v144
	global_load_dwordx4 v[236:239], v144, s[44:45]
	v_add_u32_e32 v144, 0x1000, v144
	global_load_dwordx4 v[240:243], v144, s[44:45]
	v_add_u32_e32 v144, 0x1000, v144
	global_load_dwordx4 v[84:87], v144, s[44:45]
	v_add_u32_e32 v144, 0x1000, v144
	global_load_dwordx4 v[88:91], v144, s[44:45]
	v_add_u32_e32 v144, 0x1000, v144
	global_load_dwordx4 v[92:95], v144, s[44:45]
	v_add_u32_e32 v144, 0x1000, v144
	global_load_dwordx4 v[96:99], v144, s[44:45]
